# instruction selection: accumulators zeroed with 64 v_mov_b64 instead of 128 v_mov_b32; redundant setprio 0/1 pairs between the two MFMA blocks of a segment dropped
# speedup vs baseline: 1.0074x; 1.0074x over previous
; #define PG8_STAGE(bufoff, gbase, ld) do { if ((bufoff) >= 4 * HTB) PG8_STAGE_(sRb, bufoff, gbase, ld); else PG8_STAGE_(sR, bufoff, gbase, ld); } while (0)
; #define PG8_LDA(dst, b, h) do { _Pragma("unroll") for (int m = 0; m < 4; ++m) _Pragma("unroll") for (int k = 0; k < 2; ++k) dst[m][k] = *(const LAS bf16x8*)(lds + PG8_SA(b, h) + aoff + m * 2048 + k * 1024); } while (0)
; #define PG8_LDB(dst, b, h) do { _Pragma("unroll") for (int n = 0; n < 2; ++n) _Pragma("unroll") for (int k = 0; k < 2; ++k) dst[n][k] = *(const LAS bf16x8*)(lds + PG8_SB(b, h) + boff + n * 2048 + k * 1024); } while (0)
; #define PG8_WAIT_V(n) asm volatile("s_waitcnt vmcnt(" #n ")" ::: "memory")
; #define PG8_WAIT_L(n) asm volatile("s_waitcnt lgkmcnt(" #n ")" ::: "memory")
; #define PG8_BAR __builtin_amdgcn_s_barrier()
; DI void gemm_phase(LAS unsigned char* lds, const Sched& S_, const Epi& E) {
;     ...
;     for (;;) {
;         const bool has_next = S.next(ui + 1, nxt);
;         const char* nA = has_next ? nxt.A : cA; const char* nB = has_next ? nxt.B : cB;
;         const int nlda = has_next ? nxt.lda : clda, nldb = has_next ? nxt.ldb : cldb;
;         const int nt = cur.nt;
;         const size_t hA = (size_t)HALF * clda, hB = (size_t)HALF * cldb, nhA = (size_t)HALF * nlda, nhB = (size_t)HALF * nldb;
;         for (int t = 0; t < nt; t += 2) {
;             const bool last = (t == nt - 2);
;             const char* a1 = cA + (size_t)(t + 1) * kstep;
;             const char* a2 = last ? nA : cA + (size_t)(t + 2) * kstep; const char* b2 = last ? nB : cB + (size_t)(t + 2) * kstep;
;             const char* a3 = a2 + kstep; const char* b3 = b2 + kstep;
;             const int l2a = last ? nlda : clda, l2b = last ? nldb : cldb; const size_t h2a = last ? nhA : hA, h2b = last ? nhB : hB;
;             PG8_LDB(B0, 0, 0); PG8_LDB(B1, 0, 1); PG8_SCHED; PG8_LDA(At, 0, 0); PG8_STAGE(PG8_SA(1, 1), a1 + hA, clda);
;             PG8_WAIT_V(8); PG8_WAIT_L(0); PG8_BAR; PG8_MMA(0, 0, At, B0); PG8_MMA(0, 1, At, B1); PG8_BAR; PG8_SCHED;
;     ...
; #pragma unroll
;         for (int a = 0; a < 2; ++a)
; #pragma unroll
;             for (int b = 0; b < 2; ++b)
; #pragma unroll
;                 for (int m = 0; m < 4; ++m)
; #pragma unroll
;                     for (int n = 0; n < 2; ++n) acc[a][b][m][n] = (f32x4){0.f, 0.f, 0.f, 0.f};
;         cur = nxt; cA = nA; cB = nB; clda = nlda; cldb = nldb; ++ui;
.LBB0_327:
	s_mov_b64 s[58:59], s[44:45]
	s_and_b64 s[44:45], s[28:29], exec
	s_mov_b64 s[74:75], s[50:51]
	s_mov_b32 s68, s70
	s_cselect_b32 s50, s47, s42
	s_mov_b32 s63, s57
	s_cselect_b32 s57, s59, s19
	s_cselect_b32 s70, s58, s18
	s_cselect_b32 s45, s75, s67
	s_cselect_b32 s44, s74, s66
	s_cselect_b32 s71, s68, s14
	s_ashr_i32 s43, s42, 31
	s_ashr_i32 s51, s50, 31
	s_mov_b32 s39, s47
	s_mov_b32 s23, s49
	s_mov_b32 s56, s48
	s_mov_b32 s22, s46
	s_lshl_b64 s[46:47], s[42:43], 7
	s_lshl_b64 s[48:49], s[50:51], 7
	s_add_i32 s82, s54, -2
	v_mul_lo_u32 v2, s42, v171
	v_add_u32_e32 v0, v2, v168
	v_mul_lo_u32 v4, s42, v221
	s_add_u32 s18, s18, 0x80
	v_add_u32_e32 v2, v226, v2
	v_mov_b32_e32 v3, v1
	s_waitcnt vmcnt(0)
	v_mad_u64_u32 v[132:133], s[42:43], s50, v171, v[168:169]
	v_mad_u64_u32 v[134:135], s[42:43], s50, v221, v[170:171]
	s_addc_u32 s19, s19, 0
	v_lshl_add_u64 v[136:137], s[46:47], 0, v[2:3]
	v_add_u32_e32 v2, v227, v4
	s_add_u32 s42, s66, 0x100
	v_lshl_add_u64 v[138:139], s[46:47], 0, v[2:3]
	v_mov_b32_e32 v2, 0
	s_mov_b32 s40, s81
	v_add_u32_e32 v130, v4, v170
	v_mov_b32_e32 v131, v1
	v_mov_b32_e32 v133, v1
	v_mov_b32_e32 v135, v1
	s_addc_u32 s43, s67, 0
	s_mov_b32 s83, 0
	v_mov_b64_e32 v[2:3], 0
	v_mov_b64_e32 v[4:5], 0
	v_mov_b64_e32 v[6:7], 0
	v_mov_b64_e32 v[8:9], 0
	v_mov_b64_e32 v[18:19], 0
	v_mov_b64_e32 v[20:21], 0
	v_mov_b64_e32 v[22:23], 0
	v_mov_b64_e32 v[24:25], 0
	v_mov_b64_e32 v[34:35], 0
	v_mov_b64_e32 v[36:37], 0
	v_mov_b64_e32 v[38:39], 0
	v_mov_b64_e32 v[40:41], 0
	v_mov_b64_e32 v[50:51], 0
	v_mov_b64_e32 v[52:53], 0
	v_mov_b64_e32 v[54:55], 0
	v_mov_b64_e32 v[56:57], 0
	v_mov_b64_e32 v[10:11], 0
	v_mov_b64_e32 v[12:13], 0
	v_mov_b64_e32 v[14:15], 0
	v_mov_b64_e32 v[16:17], 0
	v_mov_b64_e32 v[26:27], 0
	v_mov_b64_e32 v[28:29], 0
	v_mov_b64_e32 v[30:31], 0
	v_mov_b64_e32 v[32:33], 0
	v_mov_b64_e32 v[42:43], 0
	v_mov_b64_e32 v[44:45], 0
	v_mov_b64_e32 v[46:47], 0
	v_mov_b64_e32 v[48:49], 0
	v_mov_b64_e32 v[58:59], 0
	v_mov_b64_e32 v[60:61], 0
	v_mov_b64_e32 v[62:63], 0
	v_mov_b64_e32 v[64:65], 0
	v_mov_b64_e32 v[66:67], 0
	v_mov_b64_e32 v[68:69], 0
	v_mov_b64_e32 v[70:71], 0
	v_mov_b64_e32 v[72:73], 0
	v_mov_b64_e32 v[82:83], 0
	v_mov_b64_e32 v[84:85], 0
	v_mov_b64_e32 v[86:87], 0
	v_mov_b64_e32 v[88:89], 0
	v_mov_b64_e32 v[98:99], 0
	v_mov_b64_e32 v[100:101], 0
	v_mov_b64_e32 v[102:103], 0
	v_mov_b64_e32 v[104:105], 0
	v_mov_b64_e32 v[114:115], 0
	v_mov_b64_e32 v[116:117], 0
	v_mov_b64_e32 v[118:119], 0
	v_mov_b64_e32 v[120:121], 0
	v_mov_b64_e32 v[74:75], 0
	v_mov_b64_e32 v[76:77], 0
	v_mov_b64_e32 v[78:79], 0
	v_mov_b64_e32 v[80:81], 0
	v_mov_b64_e32 v[90:91], 0
	v_mov_b64_e32 v[92:93], 0
	v_mov_b64_e32 v[94:95], 0
	v_mov_b64_e32 v[96:97], 0
	v_mov_b64_e32 v[106:107], 0
	v_mov_b64_e32 v[108:109], 0
	v_mov_b64_e32 v[110:111], 0
	v_mov_b64_e32 v[112:113], 0
	v_mov_b64_e32 v[122:123], 0
	v_mov_b64_e32 v[124:125], 0
	v_mov_b64_e32 v[126:127], 0
	v_mov_b64_e32 v[128:129], 0
	s_branch .LBB0_329
.LBB0_328:
	s_add_i32 s83, s83, 2
	s_add_u32 s77, s18, 0x80
	s_addc_u32 s84, s19, 0
	s_and_b64 s[80:81], exec, s[80:81]
	s_cselect_b32 s81, s57, s84
	s_cselect_b32 s80, s70, s77
	s_add_i32 s86, 0, 0x10000
	s_add_i32 s89, 0, 0x14000
	v_add_u32_e32 v156, s86, v225
	v_add_u32_e32 v180, s89, v225
	ds_read_b128 v[144:147], v156
	ds_read_b128 v[148:151], v156 offset:1024
	ds_read_b128 v[152:155], v156 offset:2048
	ds_read_b128 v[156:159], v156 offset:3072
	ds_read_b128 v[160:163], v180
	ds_read_b128 v[164:167], v180 offset:1024
	ds_read_b128 v[176:179], v180 offset:2048
	ds_read_b128 v[180:183], v180 offset:3072
	s_ashr_i32 s77, s76, 31
	v_lshl_add_u64 v[208:209], s[18:19], 0, v[136:137]
	s_add_i32 m0, s31, 0xc000
	ds_read_b128 v[184:187], v228
	ds_read_b128 v[188:191], v228 offset:1024
	ds_read_b128 v[192:195], v228 offset:2048
	ds_read_b128 v[196:199], v228 offset:3072
	ds_read_b128 v[200:203], v228 offset:4096
	ds_read_b128 v[204:207], v228 offset:5120
	ds_read_b128 v[236:239], v228 offset:6144
	ds_read_b128 v[240:243], v228 offset:7168
	global_load_lds_dwordx4 v[208:209], off
	v_lshl_add_u64 v[208:209], s[18:19], 0, v[138:139]
	s_add_i32 m0, s31, 0xe000
	s_nop 0
	global_load_lds_dwordx4 v[208:209], off
	s_waitcnt vmcnt(8)
	s_waitcnt lgkmcnt(0)
	s_barrier
	s_setprio 1
	s_waitcnt lgkmcnt(0)
	v_mfma_f32_16x16x32_bf16 v[126:129], v[144:147], v[184:187], v[126:129]
	v_mfma_f32_16x16x32_bf16 v[122:125], v[152:155], v[184:187], v[122:125]
	v_mfma_f32_16x16x32_bf16 v[110:113], v[144:147], v[192:195], v[110:113]
	v_mfma_f32_16x16x32_bf16 v[106:109], v[152:155], v[192:195], v[106:109]
	v_mfma_f32_16x16x32_bf16 v[94:97], v[144:147], v[200:203], v[94:97]
	v_mfma_f32_16x16x32_bf16 v[90:93], v[152:155], v[200:203], v[90:93]
	v_mfma_f32_16x16x32_bf16 v[78:81], v[144:147], v[236:239], v[78:81]
	v_mfma_f32_16x16x32_bf16 v[74:77], v[152:155], v[236:239], v[74:77]
	v_mfma_f32_16x16x32_bf16 v[126:129], v[148:151], v[188:191], v[126:129]
	v_mfma_f32_16x16x32_bf16 v[122:125], v[156:159], v[188:191], v[122:125]
	v_mfma_f32_16x16x32_bf16 v[110:113], v[148:151], v[196:199], v[110:113]
	v_mfma_f32_16x16x32_bf16 v[106:109], v[156:159], v[196:199], v[106:109]
	v_mfma_f32_16x16x32_bf16 v[94:97], v[148:151], v[204:207], v[94:97]
	v_mfma_f32_16x16x32_bf16 v[90:93], v[156:159], v[204:207], v[90:93]
	v_mfma_f32_16x16x32_bf16 v[78:81], v[148:151], v[240:243], v[78:81]
	v_mfma_f32_16x16x32_bf16 v[74:77], v[156:159], v[240:243], v[74:77]
	v_mfma_f32_16x16x32_bf16 v[118:121], v[160:163], v[184:187], v[118:121]
	v_mfma_f32_16x16x32_bf16 v[114:117], v[176:179], v[184:187], v[114:117]
	v_mfma_f32_16x16x32_bf16 v[102:105], v[160:163], v[192:195], v[102:105]
	v_mfma_f32_16x16x32_bf16 v[98:101], v[176:179], v[192:195], v[98:101]
	v_mfma_f32_16x16x32_bf16 v[86:89], v[160:163], v[200:203], v[86:89]
	v_mfma_f32_16x16x32_bf16 v[82:85], v[176:179], v[200:203], v[82:85]
	v_mfma_f32_16x16x32_bf16 v[70:73], v[160:163], v[236:239], v[70:73]
	v_mfma_f32_16x16x32_bf16 v[66:69], v[176:179], v[236:239], v[66:69]
	v_mfma_f32_16x16x32_bf16 v[118:121], v[164:167], v[188:191], v[118:121]
	v_mfma_f32_16x16x32_bf16 v[114:117], v[180:183], v[188:191], v[114:117]
	v_mfma_f32_16x16x32_bf16 v[102:105], v[164:167], v[196:199], v[102:105]
	v_mfma_f32_16x16x32_bf16 v[98:101], v[180:183], v[196:199], v[98:101]
	v_mfma_f32_16x16x32_bf16 v[86:89], v[164:167], v[204:207], v[86:89]
	v_mfma_f32_16x16x32_bf16 v[82:85], v[180:183], v[204:207], v[82:85]
	v_mfma_f32_16x16x32_bf16 v[70:73], v[164:167], v[240:243], v[70:73]
	v_mfma_f32_16x16x32_bf16 v[66:69], v[180:183], v[240:243], v[66:69]
	s_setprio 0
	s_barrier
; #define PG8_STAGE(bufoff, gbase, ld) do { if ((bufoff) >= 4 * HTB) PG8_STAGE_(sRb, bufoff, gbase, ld); else PG8_STAGE_(sR, bufoff, gbase, ld); } while (0)
; #define PG8_LDA(dst, b, h) do { _Pragma("unroll") for (int m = 0; m < 4; ++m) _Pragma("unroll") for (int k = 0; k < 2; ++k) dst[m][k] = *(const LAS bf16x8*)(lds + PG8_SA(b, h) + aoff + m * 2048 + k * 1024); } while (0)
; #define PG8_LDB(dst, b, h) do { _Pragma("unroll") for (int n = 0; n < 2; ++n) _Pragma("unroll") for (int k = 0; k < 2; ++k) dst[n][k] = *(const LAS bf16x8*)(lds + PG8_SB(b, h) + boff + n * 2048 + k * 1024); } while (0)
; #define PG8_MMA(ai, bj, At, Bt) do { __builtin_amdgcn_s_setprio(1); _Pragma("unroll") for (int m = 0; m < 4; ++m) _Pragma("unroll") for (int n = 0; n < 2; ++n) _Pragma("unroll") for (int k = 0; k < 2; ++k) \
;         acc[ai][bj][m][n] = __builtin_amdgcn_mfma_f32_16x16x32_bf16(Bt[n][k], At[m][k], acc[ai][bj][m][n], 0, 0, 0); __builtin_amdgcn_s_setprio(0); } while (0)
; #define PG8_WAIT_V(n) asm volatile("s_waitcnt vmcnt(" #n ")" ::: "memory")
; #define PG8_WAIT_L(n) asm volatile("s_waitcnt lgkmcnt(" #n ")" ::: "memory")
; #define PG8_BAR __builtin_amdgcn_s_barrier()
; #define PG8_SCHED __builtin_amdgcn_sched_barrier(0)
; DI void gemm_phase(LAS unsigned char* lds, const Sched& S_, const Epi& E) {
;     ...
;             PG8_LDA(At, 0, 1); PG8_STAGE(PG8_SB(0, 0), b2, l2b); PG8_STAGE(PG8_SB(0, 1), b2 + h2b, l2b); PG8_STAGE(PG8_SA(0, 0), a2, l2a);
;             PG8_WAIT_V(8); PG8_WAIT_L(0); PG8_BAR; PG8_MMA(1, 0, At, B0); PG8_MMA(1, 1, At, B1); PG8_BAR; PG8_SCHED;
;             PG8_LDB(B0, 1, 0); PG8_LDB(B1, 1, 1); PG8_SCHED; PG8_LDA(At, 1, 0); PG8_STAGE(PG8_SA(0, 1), a2 + h2a, l2a);
	s_add_i32 s86, s86, s30
	v_mad_u64_u32 v[208:209], s[84:85], s76, v220, v[168:169]
	s_mov_b32 m0, s86
	ds_read_b128 v[184:187], v228 offset:16384
	ds_read_b128 v[188:191], v228 offset:17408
	ds_read_b128 v[192:195], v228 offset:18432
	ds_read_b128 v[196:199], v228 offset:19456
	ds_read_b128 v[200:203], v228 offset:20480
	ds_read_b128 v[204:207], v228 offset:21504
	ds_read_b128 v[236:239], v228 offset:22528
	ds_read_b128 v[240:243], v228 offset:23552
	global_load_lds_dwordx4 v208, s[78:79]
	v_mad_u64_u32 v[244:245], s[84:85], s76, v222, v[170:171]
	s_add_i32 m0, s86, 0x2000
	s_lshl_b64 s[76:77], s[76:77], 7
	v_mov_b32_e32 v209, v1
	v_mov_b32_e32 v245, v1
	s_add_u32 s76, s78, s76
	v_lshl_add_u64 v[230:231], s[78:79], 0, v[208:209]
	v_lshl_add_u64 v[246:247], s[78:79], 0, v[244:245]
	global_load_lds_dwordx4 v244, s[78:79]
	s_addc_u32 s77, s79, s77
	s_add_i32 s78, s89, s30
	s_mov_b32 m0, s78
	v_lshl_add_u64 v[248:249], s[76:77], 0, v[208:209]
	global_load_lds_dwordx4 v208, s[76:77]
	s_add_i32 m0, s78, 0x2000
	v_lshl_add_u64 v[208:209], s[76:77], 0, v[244:245]
	global_load_lds_dwordx4 v244, s[76:77]
	v_lshl_add_u64 v[244:245], s[80:81], 0, v[142:143]
	s_mov_b32 m0, s31
	v_lshl_add_u64 v[250:251], s[80:81], 0, v[140:141]
	global_load_lds_dwordx4 v[244:245], off
	s_mov_b32 m0, s69
	s_nop 0
	global_load_lds_dwordx4 v[250:251], off
	s_waitcnt vmcnt(8)
	s_waitcnt lgkmcnt(0)
	s_barrier
	s_setprio 1
	s_waitcnt lgkmcnt(0)
	v_mfma_f32_16x16x32_bf16 v[62:65], v[144:147], v[184:187], v[62:65]
	v_mfma_f32_16x16x32_bf16 v[58:61], v[152:155], v[184:187], v[58:61]
	v_mfma_f32_16x16x32_bf16 v[46:49], v[144:147], v[192:195], v[46:49]
	v_mfma_f32_16x16x32_bf16 v[42:45], v[152:155], v[192:195], v[42:45]
	v_mfma_f32_16x16x32_bf16 v[30:33], v[144:147], v[200:203], v[30:33]
	v_mfma_f32_16x16x32_bf16 v[26:29], v[152:155], v[200:203], v[26:29]
	v_mfma_f32_16x16x32_bf16 v[14:17], v[144:147], v[236:239], v[14:17]
	v_mfma_f32_16x16x32_bf16 v[10:13], v[152:155], v[236:239], v[10:13]
	v_mfma_f32_16x16x32_bf16 v[62:65], v[148:151], v[188:191], v[62:65]
	v_mfma_f32_16x16x32_bf16 v[58:61], v[156:159], v[188:191], v[58:61]
	v_mfma_f32_16x16x32_bf16 v[46:49], v[148:151], v[196:199], v[46:49]
	v_mfma_f32_16x16x32_bf16 v[42:45], v[156:159], v[196:199], v[42:45]
	v_mfma_f32_16x16x32_bf16 v[30:33], v[148:151], v[204:207], v[30:33]
	v_mfma_f32_16x16x32_bf16 v[26:29], v[156:159], v[204:207], v[26:29]
	v_mfma_f32_16x16x32_bf16 v[14:17], v[148:151], v[240:243], v[14:17]
	v_mfma_f32_16x16x32_bf16 v[10:13], v[156:159], v[240:243], v[10:13]
	v_mfma_f32_16x16x32_bf16 v[54:57], v[160:163], v[184:187], v[54:57]
	v_mfma_f32_16x16x32_bf16 v[50:53], v[176:179], v[184:187], v[50:53]
	v_mfma_f32_16x16x32_bf16 v[38:41], v[160:163], v[192:195], v[38:41]
	v_mfma_f32_16x16x32_bf16 v[34:37], v[176:179], v[192:195], v[34:37]
	v_mfma_f32_16x16x32_bf16 v[22:25], v[160:163], v[200:203], v[22:25]
	v_mfma_f32_16x16x32_bf16 v[18:21], v[176:179], v[200:203], v[18:21]
	v_mfma_f32_16x16x32_bf16 v[6:9], v[160:163], v[236:239], v[6:9]
	v_mfma_f32_16x16x32_bf16 v[2:5], v[176:179], v[236:239], v[2:5]
	v_mfma_f32_16x16x32_bf16 v[54:57], v[164:167], v[188:191], v[54:57]
	v_mfma_f32_16x16x32_bf16 v[50:53], v[180:183], v[188:191], v[50:53]
	v_mfma_f32_16x16x32_bf16 v[38:41], v[164:167], v[196:199], v[38:41]
	v_mfma_f32_16x16x32_bf16 v[34:37], v[180:183], v[196:199], v[34:37]
	v_mfma_f32_16x16x32_bf16 v[22:25], v[164:167], v[204:207], v[22:25]
	v_mfma_f32_16x16x32_bf16 v[18:21], v[180:183], v[204:207], v[18:21]
	v_mfma_f32_16x16x32_bf16 v[6:9], v[164:167], v[240:243], v[6:9]
	v_mfma_f32_16x16x32_bf16 v[2:5], v[180:183], v[240:243], v[2:5]
	s_setprio 0
	s_barrier
	s_add_i32 s76, 0, 0x18000
	s_add_i32 s77, 0, 0x1c000
	v_add_u32_e32 v156, s76, v225
	v_add_u32_e32 v180, s77, v225
	ds_read_b128 v[144:147], v156
	ds_read_b128 v[148:151], v156 offset:1024
	ds_read_b128 v[152:155], v156 offset:2048
	ds_read_b128 v[156:159], v156 offset:3072
	ds_read_b128 v[160:163], v180
	ds_read_b128 v[164:167], v180 offset:1024
	ds_read_b128 v[176:179], v180 offset:2048
	ds_read_b128 v[180:183], v180 offset:3072
	s_add_u32 s50, s80, s50
	s_addc_u32 s51, s81, s51
	s_mov_b32 m0, s90
	v_lshl_add_u64 v[142:143], s[50:51], 0, v[142:143]
	ds_read_b128 v[184:187], v228 offset:32768
	ds_read_b128 v[188:191], v228 offset:33792
	ds_read_b128 v[192:195], v228 offset:34816
	ds_read_b128 v[196:199], v228 offset:35840
	ds_read_b128 v[200:203], v228 offset:36864
	ds_read_b128 v[204:207], v228 offset:37888
	ds_read_b128 v[236:239], v228 offset:38912
	ds_read_b128 v[240:243], v228 offset:39936
	global_load_lds_dwordx4 v[142:143], off
	v_lshl_add_u64 v[140:141], s[50:51], 0, v[140:141]
	s_mov_b32 m0, s91
	s_nop 0
	global_load_lds_dwordx4 v[140:141], off
	s_waitcnt vmcnt(8)
	s_waitcnt lgkmcnt(0)
	s_barrier
; #define PG8_STAGE(bufoff, gbase, ld) do { if ((bufoff) >= 4 * HTB) PG8_STAGE_(sRb, bufoff, gbase, ld); else PG8_STAGE_(sR, bufoff, gbase, ld); } while (0)
; #define PG8_LDA(dst, b, h) do { _Pragma("unroll") for (int m = 0; m < 4; ++m) _Pragma("unroll") for (int k = 0; k < 2; ++k) dst[m][k] = *(const LAS bf16x8*)(lds + PG8_SA(b, h) + aoff + m * 2048 + k * 1024); } while (0)
; #define PG8_LDB(dst, b, h) do { _Pragma("unroll") for (int n = 0; n < 2; ++n) _Pragma("unroll") for (int k = 0; k < 2; ++k) dst[n][k] = *(const LAS bf16x8*)(lds + PG8_SB(b, h) + boff + n * 2048 + k * 1024); } while (0)
; #define PG8_MMA(ai, bj, At, Bt) do { __builtin_amdgcn_s_setprio(1); _Pragma("unroll") for (int m = 0; m < 4; ++m) _Pragma("unroll") for (int n = 0; n < 2; ++n) _Pragma("unroll") for (int k = 0; k < 2; ++k) \
;         acc[ai][bj][m][n] = __builtin_amdgcn_mfma_f32_16x16x32_bf16(Bt[n][k], At[m][k], acc[ai][bj][m][n], 0, 0, 0); __builtin_amdgcn_s_setprio(0); } while (0)
; #define PG8_WAIT_V(n) asm volatile("s_waitcnt vmcnt(" #n ")" ::: "memory")
; #define PG8_WAIT_L(n) asm volatile("s_waitcnt lgkmcnt(" #n ")" ::: "memory")
; #define PG8_BAR __builtin_amdgcn_s_barrier()
; #define PG8_SCHED __builtin_amdgcn_sched_barrier(0)
; DI void gemm_phase(LAS unsigned char* lds, const Sched& S_, const Epi& E) {
;     ...
;             PG8_LDB(B0, 1, 0); PG8_LDB(B1, 1, 1); PG8_SCHED; PG8_LDA(At, 1, 0); PG8_STAGE(PG8_SA(0, 1), a2 + h2a, l2a);
;             PG8_WAIT_V(8); PG8_WAIT_L(0); PG8_BAR; PG8_MMA(0, 0, At, B0); PG8_MMA(0, 1, At, B1); PG8_BAR; PG8_SCHED;
;             PG8_LDA(At, 1, 1); PG8_STAGE(PG8_SB(1, 0), b3, l2b); PG8_STAGE(PG8_SB(1, 1), b3 + h2b, l2b); PG8_STAGE(PG8_SA(1, 0), a3, l2a);
;             PG8_WAIT_V(8); PG8_WAIT_L(0); PG8_BAR; PG8_MMA(1, 0, At, B0); PG8_MMA(1, 1, At, B1); PG8_BAR; PG8_SCHED;
	s_setprio 1
	s_waitcnt lgkmcnt(0)
	v_mfma_f32_16x16x32_bf16 v[126:129], v[144:147], v[184:187], v[126:129]
	v_mfma_f32_16x16x32_bf16 v[122:125], v[152:155], v[184:187], v[122:125]
	v_mfma_f32_16x16x32_bf16 v[110:113], v[144:147], v[192:195], v[110:113]
	v_mfma_f32_16x16x32_bf16 v[106:109], v[152:155], v[192:195], v[106:109]
	v_mfma_f32_16x16x32_bf16 v[94:97], v[144:147], v[200:203], v[94:97]
	v_mfma_f32_16x16x32_bf16 v[90:93], v[152:155], v[200:203], v[90:93]
	v_mfma_f32_16x16x32_bf16 v[78:81], v[144:147], v[236:239], v[78:81]
	v_mfma_f32_16x16x32_bf16 v[74:77], v[152:155], v[236:239], v[74:77]
	v_mfma_f32_16x16x32_bf16 v[126:129], v[148:151], v[188:191], v[126:129]
	v_mfma_f32_16x16x32_bf16 v[122:125], v[156:159], v[188:191], v[122:125]
	v_mfma_f32_16x16x32_bf16 v[110:113], v[148:151], v[196:199], v[110:113]
	v_mfma_f32_16x16x32_bf16 v[106:109], v[156:159], v[196:199], v[106:109]
	v_mfma_f32_16x16x32_bf16 v[94:97], v[148:151], v[204:207], v[94:97]
	v_mfma_f32_16x16x32_bf16 v[90:93], v[156:159], v[204:207], v[90:93]
	v_mfma_f32_16x16x32_bf16 v[78:81], v[148:151], v[240:243], v[78:81]
	v_mfma_f32_16x16x32_bf16 v[74:77], v[156:159], v[240:243], v[74:77]
	v_mfma_f32_16x16x32_bf16 v[118:121], v[160:163], v[184:187], v[118:121]
	v_mfma_f32_16x16x32_bf16 v[114:117], v[176:179], v[184:187], v[114:117]
	v_mfma_f32_16x16x32_bf16 v[102:105], v[160:163], v[192:195], v[102:105]
	v_mfma_f32_16x16x32_bf16 v[98:101], v[176:179], v[192:195], v[98:101]
	v_mfma_f32_16x16x32_bf16 v[86:89], v[160:163], v[200:203], v[86:89]
	v_mfma_f32_16x16x32_bf16 v[82:85], v[176:179], v[200:203], v[82:85]
	v_mfma_f32_16x16x32_bf16 v[70:73], v[160:163], v[236:239], v[70:73]
	v_mfma_f32_16x16x32_bf16 v[66:69], v[176:179], v[236:239], v[66:69]
	v_mfma_f32_16x16x32_bf16 v[118:121], v[164:167], v[188:191], v[118:121]
	v_mfma_f32_16x16x32_bf16 v[114:117], v[180:183], v[188:191], v[114:117]
	v_mfma_f32_16x16x32_bf16 v[102:105], v[164:167], v[196:199], v[102:105]
	v_mfma_f32_16x16x32_bf16 v[98:101], v[180:183], v[196:199], v[98:101]
	v_mfma_f32_16x16x32_bf16 v[86:89], v[164:167], v[204:207], v[86:89]
	v_mfma_f32_16x16x32_bf16 v[82:85], v[180:183], v[204:207], v[82:85]
	v_mfma_f32_16x16x32_bf16 v[70:73], v[164:167], v[240:243], v[70:73]
	v_mfma_f32_16x16x32_bf16 v[66:69], v[180:183], v[240:243], v[66:69]
	s_setprio 0
	s_barrier
	s_add_i32 s50, s76, s30
	v_lshl_add_u64 v[230:231], v[230:231], 0, s[34:35]
	s_mov_b32 m0, s50
	ds_read_b128 v[140:143], v228 offset:49152
	ds_read_b128 v[184:187], v228 offset:50176
	ds_read_b128 v[188:191], v228 offset:51200
	ds_read_b128 v[192:195], v228 offset:52224
	ds_read_b128 v[196:199], v228 offset:53248
	ds_read_b128 v[200:203], v228 offset:54272
	ds_read_b128 v[204:207], v228 offset:55296
	ds_read_b128 v[236:239], v228 offset:56320
	global_load_lds_dwordx4 v[230:231], off
	v_lshl_add_u64 v[230:231], v[246:247], 0, s[34:35]
	s_add_i32 m0, s50, 0x2000
	s_add_i32 s50, s77, s30
	global_load_lds_dwordx4 v[230:231], off
	v_lshl_add_u64 v[230:231], v[248:249], 0, s[34:35]
	s_mov_b32 m0, s50
	v_lshl_add_u64 v[208:209], v[208:209], 0, s[34:35]
	global_load_lds_dwordx4 v[230:231], off
	s_add_i32 m0, s50, 0x2000
	s_nop 0
	global_load_lds_dwordx4 v[208:209], off
	v_lshl_add_u64 v[208:209], v[244:245], 0, s[34:35]
	s_mov_b32 m0, s25
	s_nop 0
	global_load_lds_dwordx4 v[208:209], off
	v_lshl_add_u64 v[208:209], v[250:251], 0, s[34:35]
	s_mov_b32 m0, s26
	s_nop 0
	global_load_lds_dwordx4 v[208:209], off
	s_waitcnt vmcnt(8)
	s_waitcnt lgkmcnt(0)
	s_barrier
	s_setprio 1
	s_waitcnt lgkmcnt(0)
	v_mfma_f32_16x16x32_bf16 v[62:65], v[144:147], v[140:143], v[62:65]
	v_mfma_f32_16x16x32_bf16 v[58:61], v[152:155], v[140:143], v[58:61]
	v_mfma_f32_16x16x32_bf16 v[46:49], v[144:147], v[188:191], v[46:49]
	v_mfma_f32_16x16x32_bf16 v[42:45], v[152:155], v[188:191], v[42:45]
	v_mfma_f32_16x16x32_bf16 v[30:33], v[144:147], v[196:199], v[30:33]
	v_mfma_f32_16x16x32_bf16 v[26:29], v[152:155], v[196:199], v[26:29]
	v_mfma_f32_16x16x32_bf16 v[14:17], v[144:147], v[204:207], v[14:17]
	v_mfma_f32_16x16x32_bf16 v[10:13], v[152:155], v[204:207], v[10:13]
	v_mfma_f32_16x16x32_bf16 v[62:65], v[148:151], v[184:187], v[62:65]
	v_mfma_f32_16x16x32_bf16 v[58:61], v[156:159], v[184:187], v[58:61]
	v_mfma_f32_16x16x32_bf16 v[46:49], v[148:151], v[192:195], v[46:49]
	v_mfma_f32_16x16x32_bf16 v[42:45], v[156:159], v[192:195], v[42:45]
	v_mfma_f32_16x16x32_bf16 v[30:33], v[148:151], v[200:203], v[30:33]
	v_mfma_f32_16x16x32_bf16 v[26:29], v[156:159], v[200:203], v[26:29]
	v_mfma_f32_16x16x32_bf16 v[14:17], v[148:151], v[236:239], v[14:17]
	v_mfma_f32_16x16x32_bf16 v[10:13], v[156:159], v[236:239], v[10:13]
	v_mfma_f32_16x16x32_bf16 v[54:57], v[160:163], v[140:143], v[54:57]
	v_mfma_f32_16x16x32_bf16 v[50:53], v[176:179], v[140:143], v[50:53]
	v_mfma_f32_16x16x32_bf16 v[38:41], v[160:163], v[188:191], v[38:41]
	v_mfma_f32_16x16x32_bf16 v[34:37], v[176:179], v[188:191], v[34:37]
	v_mfma_f32_16x16x32_bf16 v[22:25], v[160:163], v[196:199], v[22:25]
	v_mfma_f32_16x16x32_bf16 v[18:21], v[176:179], v[196:199], v[18:21]
	v_mfma_f32_16x16x32_bf16 v[6:9], v[160:163], v[204:207], v[6:9]
	v_mfma_f32_16x16x32_bf16 v[2:5], v[176:179], v[204:207], v[2:5]
	v_mfma_f32_16x16x32_bf16 v[54:57], v[164:167], v[184:187], v[54:57]
	v_mfma_f32_16x16x32_bf16 v[50:53], v[180:183], v[184:187], v[50:53]
	v_mfma_f32_16x16x32_bf16 v[38:41], v[164:167], v[192:195], v[38:41]
	v_mfma_f32_16x16x32_bf16 v[34:37], v[180:183], v[192:195], v[34:37]
	v_mfma_f32_16x16x32_bf16 v[22:25], v[164:167], v[200:203], v[22:25]
	v_mfma_f32_16x16x32_bf16 v[18:21], v[180:183], v[200:203], v[18:21]
	v_mfma_f32_16x16x32_bf16 v[6:9], v[164:167], v[236:239], v[6:9]
	v_mfma_f32_16x16x32_bf16 v[2:5], v[180:183], v[236:239], v[2:5]
	s_setprio 0
	s_barrier
	s_add_u32 s18, s18, 0x100
	s_addc_u32 s19, s19, 0
	s_add_u32 s42, s42, 0x100
	s_addc_u32 s43, s43, 0
	s_cmp_ge_i32 s83, s54
	s_cbranch_scc1 .LBB0_331
